# hand-written conv pre-stage (GLU/dwconv31/LayerNorm/silu): weights in regs, next-tile prefetch, DPP wave sums, 2 barriers per tile, XCD-contiguous tile order
# speedup vs baseline: 1.0323x; 1.0068x over previous
.LBB0_356:
	s_or_b64 exec, exec, s[68:69]
	s_and_b64 s[0:1], s[90:91], exec
	s_movk_i32 s0, 0x440
	s_cselect_b32 s5, 0x400, s0
	v_readlane_b32 s0, v253, 0
	v_readlane_b32 s20, v253, 30
	v_readlane_b32 s21, v253, 31
	v_readlane_b32 s22, v253, 32
	v_readlane_b32 s23, v253, 33
	s_and_b32 s1, s0, 7
	s_lshl_b32 s1, s1, 5
	s_lshr_b32 s0, s0, 3
	s_add_u32 s4, s1, s0
	v_and_b32_e32 v242, 31, v143
	v_lshrrev_b32_e32 v241, 5, v143
	v_mul_u32_u24_e32 v228, 0x1440, v241
	v_lshl_add_u32 v228, v242, 4, v228
	v_add_u32_e32 v228, 0x840, v228
	v_add_u32_e32 v229, 0x14400, v228
	v_add_u32_e32 v230, 0x28800, v228
	v_add_u32_e32 v231, 0x3cc00, v228
	v_lshlrev_b32_e32 v232, 10, v241
	v_lshl_add_u32 v232, v242, 5, v232
	v_and_b32_e32 v243, 0xff, v143
	v_lshrrev_b32_e32 v244, 8, v143
	v_lshlrev_b32_e32 v237, 14, v244
	v_lshl_add_u32 v237, v243, 2, v237
	v_add_u32_e32 v238, 0x10000, v237
	v_and_b32_e32 v245, 63, v143
	v_lshrrev_b32_e32 v246, 6, v143
	v_lshlrev_b32_e32 v239, 12, v246
	v_lshl_add_u32 v239, v245, 4, v239
	v_add_u32_e32 v239, 0x10000, v239
	v_lshlrev_b32_e32 v240, 11, v246
	v_lshl_add_u32 v240, v245, 3, v240
	v_lshlrev_b32_e32 v247, 2, v243
	v_lshlrev_b32_e32 v248, 4, v245
	s_sub_u32 s16, s4, 0x400
	s_lshr_b32 s17, s16, 3
	s_lshl_b32 s17, s17, 8
	s_add_u32 s17, s17, 0x8000
	s_and_b32 s16, s16, 7
	s_lshr_b32 s14, s4, 7
	s_lshl_b32 s14, s14, 12
	s_and_b32 s15, s4, 0x7f
	s_cmp_lt_u32 s4, 0x400
	s_cselect_b32 s14, s14, s17
	s_cselect_b32 s15, s15, s16
	s_movk_i32 s16, 0x100
	s_cselect_b32 s10, 0x1000, s16
	s_lshl_b32 s15, s15, 5
	s_add_u32 s14, s14, s15
	s_sub_u32 s16, s14, 15
	s_mul_i32 s16, s16, 0x1440
	s_ashr_i32 s17, s16, 31
	s_add_u32 s6, s50, s16
	s_addc_u32 s7, s51, s17
	s_add_u32 s6, s6, 0x5cbd000
	s_addc_u32 s7, s7, 0
	global_load_dwordx4 v[188:191], v228, s[6:7]
	global_load_dwordx4 v[192:195], v228, s[6:7] offset:512
	global_load_dwordx4 v[196:199], v229, s[6:7]
	global_load_dwordx4 v[200:203], v229, s[6:7] offset:512
	global_load_dwordx4 v[204:207], v230, s[6:7]
	global_load_dwordx4 v[208:211], v230, s[6:7] offset:512
	global_load_dwordx4 v[212:215], v231, s[6:7]
	global_load_dwordx4 v[216:219], v231, s[6:7] offset:512
	s_mul_i32 s0, s74, 0x7c00
	s_add_u32 s20, s20, s0
	s_addc_u32 s21, s21, 0
	global_load_dword v96, v247, s[20:21] offset:0
	global_load_dword v97, v247, s[20:21] offset:1024
	global_load_dword v98, v247, s[20:21] offset:2048
	global_load_dword v99, v247, s[20:21] offset:3072
	s_add_u32 s20, s20, 0x1000
	s_addc_u32 s21, s21, 0
	global_load_dword v100, v247, s[20:21] offset:0
	global_load_dword v101, v247, s[20:21] offset:1024
	global_load_dword v102, v247, s[20:21] offset:2048
	global_load_dword v103, v247, s[20:21] offset:3072
	s_add_u32 s20, s20, 0x1000
	s_addc_u32 s21, s21, 0
	global_load_dword v104, v247, s[20:21] offset:0
	global_load_dword v105, v247, s[20:21] offset:1024
	global_load_dword v106, v247, s[20:21] offset:2048
	global_load_dword v107, v247, s[20:21] offset:3072
	s_add_u32 s20, s20, 0x1000
	s_addc_u32 s21, s21, 0
	global_load_dword v108, v247, s[20:21] offset:0
	global_load_dword v109, v247, s[20:21] offset:1024
	global_load_dword v110, v247, s[20:21] offset:2048
	global_load_dword v111, v247, s[20:21] offset:3072
	s_add_u32 s20, s20, 0x1000
	s_addc_u32 s21, s21, 0
	global_load_dword v112, v247, s[20:21] offset:0
	global_load_dword v113, v247, s[20:21] offset:1024
	global_load_dword v114, v247, s[20:21] offset:2048
	global_load_dword v115, v247, s[20:21] offset:3072
	s_add_u32 s20, s20, 0x1000
	s_addc_u32 s21, s21, 0
	global_load_dword v116, v247, s[20:21] offset:0
	global_load_dword v117, v247, s[20:21] offset:1024
	global_load_dword v118, v247, s[20:21] offset:2048
	global_load_dword v119, v247, s[20:21] offset:3072
	s_add_u32 s20, s20, 0x1000
	s_addc_u32 s21, s21, 0
	global_load_dword v120, v247, s[20:21] offset:0
	global_load_dword v121, v247, s[20:21] offset:1024
	global_load_dword v122, v247, s[20:21] offset:2048
	global_load_dword v123, v247, s[20:21] offset:3072
	s_add_u32 s20, s20, 0x1000
	s_addc_u32 s21, s21, 0
	global_load_dword v124, v247, s[20:21] offset:0
	global_load_dword v125, v247, s[20:21] offset:1024
	global_load_dword v126, v247, s[20:21] offset:2048
	s_lshl_b32 s0, s74, 10
	s_add_u32 s22, s22, s0
	s_addc_u32 s23, s23, 0
	global_load_dword v127, v247, s[22:23]
	s_add_u32 s16, s36, s0
	s_addc_u32 s17, s37, 0
	global_load_dwordx4 v[220:223], v248, s[16:17]
	s_add_u32 s18, s38, s0
	s_addc_u32 s19, s39, 0
	global_load_dwordx4 v[224:227], v248, s[18:19]
	s_waitcnt vmcnt(0)
.Lcv_loop:
	s_sub_u32 s16, s4, 0x400
	s_lshr_b32 s17, s16, 3
	s_lshl_b32 s17, s17, 8
	s_add_u32 s17, s17, 0x8000
	s_and_b32 s16, s16, 7
	s_lshr_b32 s14, s4, 7
	s_lshl_b32 s14, s14, 12
	s_and_b32 s15, s4, 0x7f
	s_cmp_lt_u32 s4, 0x400
	s_cselect_b32 s14, s14, s17
	s_cselect_b32 s15, s15, s16
	s_movk_i32 s16, 0x100
	s_cselect_b32 s10, 0x1000, s16
	s_lshl_b32 s15, s15, 5
	s_add_u32 s14, s14, s15
	s_sub_u32 s11, s15, 15
	s_cmp_eq_u32 s15, 0
	s_cselect_b32 s12, 1, 0
	s_add_u32 s16, s15, 47
	s_cmp_ge_u32 s16, s10
	s_cselect_b32 s16, 1, 0
	s_or_b32 s12, s12, s16
	s_lshl_b32 s16, s14, 9
	s_add_u32 s8, s50, s16
	s_addc_u32 s9, s51, 0
	s_add_u32 s8, s8, 0x1995d000
	s_addc_u32 s9, s9, 0
	s_waitcnt vmcnt(10)
	s_cmp_eq_u32 s12, 0
	s_cbranch_scc1 .Lcv_nm0
	s_add_u32 s0, s11, 0
	v_add_u32_e32 v242, s0, v241
	v_cmp_gt_u32_e32 vcc, s10, v242
	s_nop 1
	v_cndmask_b32_e32 v188, 0, v188, vcc
	v_cndmask_b32_e32 v189, 0, v189, vcc
	v_cndmask_b32_e32 v190, 0, v190, vcc
	v_cndmask_b32_e32 v191, 0, v191, vcc
	v_cndmask_b32_e32 v192, 0, v192, vcc
	v_cndmask_b32_e32 v193, 0, v193, vcc
	v_cndmask_b32_e32 v194, 0, v194, vcc
	v_cndmask_b32_e32 v195, 0, v195, vcc
.Lcv_nm0:
	v_lshlrev_b32_e32 v16, 16, v192
	v_and_b32_e32 v17, 0xffff0000, v192
	v_lshlrev_b32_e32 v18, 16, v193
	v_and_b32_e32 v19, 0xffff0000, v193
	v_lshlrev_b32_e32 v20, 16, v194
	v_and_b32_e32 v21, 0xffff0000, v194
	v_lshlrev_b32_e32 v22, 16, v195
	v_and_b32_e32 v23, 0xffff0000, v195
	v_mul_f32_e32 v16, 0xbfb8aa3b, v16
	v_mul_f32_e32 v17, 0xbfb8aa3b, v17
	v_mul_f32_e32 v18, 0xbfb8aa3b, v18
	v_mul_f32_e32 v19, 0xbfb8aa3b, v19
	v_mul_f32_e32 v20, 0xbfb8aa3b, v20
	v_mul_f32_e32 v21, 0xbfb8aa3b, v21
	v_mul_f32_e32 v22, 0xbfb8aa3b, v22
	v_mul_f32_e32 v23, 0xbfb8aa3b, v23
	v_exp_f32_e32 v16, v16
	v_exp_f32_e32 v17, v17
	v_exp_f32_e32 v18, v18
	v_exp_f32_e32 v19, v19
	v_exp_f32_e32 v20, v20
	v_exp_f32_e32 v21, v21
	v_exp_f32_e32 v22, v22
	v_exp_f32_e32 v23, v23
	v_add_f32_e32 v16, 1.0, v16
	v_add_f32_e32 v17, 1.0, v17
	v_add_f32_e32 v18, 1.0, v18
	v_add_f32_e32 v19, 1.0, v19
	v_add_f32_e32 v20, 1.0, v20
	v_add_f32_e32 v21, 1.0, v21
	v_add_f32_e32 v22, 1.0, v22
	v_add_f32_e32 v23, 1.0, v23
	v_rcp_f32_e32 v16, v16
	v_rcp_f32_e32 v17, v17
	v_rcp_f32_e32 v18, v18
	v_rcp_f32_e32 v19, v19
	v_rcp_f32_e32 v20, v20
	v_rcp_f32_e32 v21, v21
	v_rcp_f32_e32 v22, v22
	v_rcp_f32_e32 v23, v23
	v_lshlrev_b32_e32 v24, 16, v188
	v_and_b32_e32 v25, 0xffff0000, v188
	v_lshlrev_b32_e32 v26, 16, v189
	v_and_b32_e32 v27, 0xffff0000, v189
	v_lshlrev_b32_e32 v28, 16, v190
	v_and_b32_e32 v29, 0xffff0000, v190
	v_lshlrev_b32_e32 v30, 16, v191
	v_and_b32_e32 v31, 0xffff0000, v191
	v_mul_f32_e32 v24, v24, v16
	v_mul_f32_e32 v25, v25, v17
	v_mul_f32_e32 v26, v26, v18
	v_mul_f32_e32 v27, v27, v19
	v_mul_f32_e32 v28, v28, v20
	v_mul_f32_e32 v29, v29, v21
	v_mul_f32_e32 v30, v30, v22
	v_mul_f32_e32 v31, v31, v23
	ds_write_b128 v232, v[24:27] offset:0
	ds_write_b128 v232, v[28:31] offset:16
	s_waitcnt vmcnt(8)
	s_cmp_eq_u32 s12, 0
	s_cbranch_scc1 .Lcv_nm1
	s_add_u32 s0, s11, 16
	v_add_u32_e32 v242, s0, v241
	v_cmp_gt_u32_e32 vcc, s10, v242
	s_nop 1
	v_cndmask_b32_e32 v196, 0, v196, vcc
	v_cndmask_b32_e32 v197, 0, v197, vcc
	v_cndmask_b32_e32 v198, 0, v198, vcc
	v_cndmask_b32_e32 v199, 0, v199, vcc
	v_cndmask_b32_e32 v200, 0, v200, vcc
	v_cndmask_b32_e32 v201, 0, v201, vcc
	v_cndmask_b32_e32 v202, 0, v202, vcc
	v_cndmask_b32_e32 v203, 0, v203, vcc
.Lcv_nm1:
	v_lshlrev_b32_e32 v16, 16, v200
	v_and_b32_e32 v17, 0xffff0000, v200
	v_lshlrev_b32_e32 v18, 16, v201
	v_and_b32_e32 v19, 0xffff0000, v201
	v_lshlrev_b32_e32 v20, 16, v202
	v_and_b32_e32 v21, 0xffff0000, v202
	v_lshlrev_b32_e32 v22, 16, v203
	v_and_b32_e32 v23, 0xffff0000, v203
	v_mul_f32_e32 v16, 0xbfb8aa3b, v16
	v_mul_f32_e32 v17, 0xbfb8aa3b, v17
	v_mul_f32_e32 v18, 0xbfb8aa3b, v18
	v_mul_f32_e32 v19, 0xbfb8aa3b, v19
	v_mul_f32_e32 v20, 0xbfb8aa3b, v20
	v_mul_f32_e32 v21, 0xbfb8aa3b, v21
	v_mul_f32_e32 v22, 0xbfb8aa3b, v22
	v_mul_f32_e32 v23, 0xbfb8aa3b, v23
	v_exp_f32_e32 v16, v16
	v_exp_f32_e32 v17, v17
	v_exp_f32_e32 v18, v18
	v_exp_f32_e32 v19, v19
	v_exp_f32_e32 v20, v20
	v_exp_f32_e32 v21, v21
	v_exp_f32_e32 v22, v22
	v_exp_f32_e32 v23, v23
	v_add_f32_e32 v16, 1.0, v16
	v_add_f32_e32 v17, 1.0, v17
	v_add_f32_e32 v18, 1.0, v18
	v_add_f32_e32 v19, 1.0, v19
	v_add_f32_e32 v20, 1.0, v20
	v_add_f32_e32 v21, 1.0, v21
	v_add_f32_e32 v22, 1.0, v22
	v_add_f32_e32 v23, 1.0, v23
	v_rcp_f32_e32 v16, v16
	v_rcp_f32_e32 v17, v17
	v_rcp_f32_e32 v18, v18
	v_rcp_f32_e32 v19, v19
	v_rcp_f32_e32 v20, v20
	v_rcp_f32_e32 v21, v21
	v_rcp_f32_e32 v22, v22
	v_rcp_f32_e32 v23, v23
	v_lshlrev_b32_e32 v24, 16, v196
	v_and_b32_e32 v25, 0xffff0000, v196
	v_lshlrev_b32_e32 v26, 16, v197
	v_and_b32_e32 v27, 0xffff0000, v197
	v_lshlrev_b32_e32 v28, 16, v198
	v_and_b32_e32 v29, 0xffff0000, v198
	v_lshlrev_b32_e32 v30, 16, v199
	v_and_b32_e32 v31, 0xffff0000, v199
	v_mul_f32_e32 v24, v24, v16
	v_mul_f32_e32 v25, v25, v17
	v_mul_f32_e32 v26, v26, v18
	v_mul_f32_e32 v27, v27, v19
	v_mul_f32_e32 v28, v28, v20
	v_mul_f32_e32 v29, v29, v21
	v_mul_f32_e32 v30, v30, v22
	v_mul_f32_e32 v31, v31, v23
	ds_write_b128 v232, v[24:27] offset:16384
	ds_write_b128 v232, v[28:31] offset:16400
	s_waitcnt vmcnt(6)
	s_cmp_eq_u32 s12, 0
	s_cbranch_scc1 .Lcv_nm2
	s_add_u32 s0, s11, 32
	v_add_u32_e32 v242, s0, v241
	v_cmp_gt_u32_e32 vcc, s10, v242
	s_nop 1
	v_cndmask_b32_e32 v204, 0, v204, vcc
	v_cndmask_b32_e32 v205, 0, v205, vcc
	v_cndmask_b32_e32 v206, 0, v206, vcc
	v_cndmask_b32_e32 v207, 0, v207, vcc
	v_cndmask_b32_e32 v208, 0, v208, vcc
	v_cndmask_b32_e32 v209, 0, v209, vcc
	v_cndmask_b32_e32 v210, 0, v210, vcc
	v_cndmask_b32_e32 v211, 0, v211, vcc
.Lcv_nm2:
	v_lshlrev_b32_e32 v16, 16, v208
	v_and_b32_e32 v17, 0xffff0000, v208
	v_lshlrev_b32_e32 v18, 16, v209
	v_and_b32_e32 v19, 0xffff0000, v209
	v_lshlrev_b32_e32 v20, 16, v210
	v_and_b32_e32 v21, 0xffff0000, v210
	v_lshlrev_b32_e32 v22, 16, v211
	v_and_b32_e32 v23, 0xffff0000, v211
	v_mul_f32_e32 v16, 0xbfb8aa3b, v16
	v_mul_f32_e32 v17, 0xbfb8aa3b, v17
	v_mul_f32_e32 v18, 0xbfb8aa3b, v18
	v_mul_f32_e32 v19, 0xbfb8aa3b, v19
	v_mul_f32_e32 v20, 0xbfb8aa3b, v20
	v_mul_f32_e32 v21, 0xbfb8aa3b, v21
	v_mul_f32_e32 v22, 0xbfb8aa3b, v22
	v_mul_f32_e32 v23, 0xbfb8aa3b, v23
	v_exp_f32_e32 v16, v16
	v_exp_f32_e32 v17, v17
	v_exp_f32_e32 v18, v18
	v_exp_f32_e32 v19, v19
	v_exp_f32_e32 v20, v20
	v_exp_f32_e32 v21, v21
	v_exp_f32_e32 v22, v22
	v_exp_f32_e32 v23, v23
	v_add_f32_e32 v16, 1.0, v16
	v_add_f32_e32 v17, 1.0, v17
	v_add_f32_e32 v18, 1.0, v18
	v_add_f32_e32 v19, 1.0, v19
	v_add_f32_e32 v20, 1.0, v20
	v_add_f32_e32 v21, 1.0, v21
	v_add_f32_e32 v22, 1.0, v22
	v_add_f32_e32 v23, 1.0, v23
	v_rcp_f32_e32 v16, v16
	v_rcp_f32_e32 v17, v17
	v_rcp_f32_e32 v18, v18
	v_rcp_f32_e32 v19, v19
	v_rcp_f32_e32 v20, v20
	v_rcp_f32_e32 v21, v21
	v_rcp_f32_e32 v22, v22
	v_rcp_f32_e32 v23, v23
	v_lshlrev_b32_e32 v24, 16, v204
	v_and_b32_e32 v25, 0xffff0000, v204
	v_lshlrev_b32_e32 v26, 16, v205
	v_and_b32_e32 v27, 0xffff0000, v205
	v_lshlrev_b32_e32 v28, 16, v206
	v_and_b32_e32 v29, 0xffff0000, v206
	v_lshlrev_b32_e32 v30, 16, v207
	v_and_b32_e32 v31, 0xffff0000, v207
	v_mul_f32_e32 v24, v24, v16
	v_mul_f32_e32 v25, v25, v17
	v_mul_f32_e32 v26, v26, v18
	v_mul_f32_e32 v27, v27, v19
	v_mul_f32_e32 v28, v28, v20
	v_mul_f32_e32 v29, v29, v21
	v_mul_f32_e32 v30, v30, v22
	v_mul_f32_e32 v31, v31, v23
	ds_write_b128 v232, v[24:27] offset:32768
	ds_write_b128 v232, v[28:31] offset:32784
	s_waitcnt vmcnt(4)
	s_cmp_eq_u32 s12, 0
	s_cbranch_scc1 .Lcv_nm3
	s_add_u32 s0, s11, 48
	v_add_u32_e32 v242, s0, v241
	v_cmp_gt_u32_e32 vcc, s10, v242
	s_nop 1
	v_cndmask_b32_e32 v212, 0, v212, vcc
	v_cndmask_b32_e32 v213, 0, v213, vcc
	v_cndmask_b32_e32 v214, 0, v214, vcc
	v_cndmask_b32_e32 v215, 0, v215, vcc
	v_cndmask_b32_e32 v216, 0, v216, vcc
	v_cndmask_b32_e32 v217, 0, v217, vcc
	v_cndmask_b32_e32 v218, 0, v218, vcc
	v_cndmask_b32_e32 v219, 0, v219, vcc
.Lcv_nm3:
	v_lshlrev_b32_e32 v16, 16, v216
	v_and_b32_e32 v17, 0xffff0000, v216
	v_lshlrev_b32_e32 v18, 16, v217
	v_and_b32_e32 v19, 0xffff0000, v217
	v_lshlrev_b32_e32 v20, 16, v218
	v_and_b32_e32 v21, 0xffff0000, v218
	v_lshlrev_b32_e32 v22, 16, v219
	v_and_b32_e32 v23, 0xffff0000, v219
	v_mul_f32_e32 v16, 0xbfb8aa3b, v16
	v_mul_f32_e32 v17, 0xbfb8aa3b, v17
	v_mul_f32_e32 v18, 0xbfb8aa3b, v18
	v_mul_f32_e32 v19, 0xbfb8aa3b, v19
	v_mul_f32_e32 v20, 0xbfb8aa3b, v20
	v_mul_f32_e32 v21, 0xbfb8aa3b, v21
	v_mul_f32_e32 v22, 0xbfb8aa3b, v22
	v_mul_f32_e32 v23, 0xbfb8aa3b, v23
	v_exp_f32_e32 v16, v16
	v_exp_f32_e32 v17, v17
	v_exp_f32_e32 v18, v18
	v_exp_f32_e32 v19, v19
	v_exp_f32_e32 v20, v20
	v_exp_f32_e32 v21, v21
	v_exp_f32_e32 v22, v22
	v_exp_f32_e32 v23, v23
	v_add_f32_e32 v16, 1.0, v16
	v_add_f32_e32 v17, 1.0, v17
	v_add_f32_e32 v18, 1.0, v18
	v_add_f32_e32 v19, 1.0, v19
	v_add_f32_e32 v20, 1.0, v20
	v_add_f32_e32 v21, 1.0, v21
	v_add_f32_e32 v22, 1.0, v22
	v_add_f32_e32 v23, 1.0, v23
	v_rcp_f32_e32 v16, v16
	v_rcp_f32_e32 v17, v17
	v_rcp_f32_e32 v18, v18
	v_rcp_f32_e32 v19, v19
	v_rcp_f32_e32 v20, v20
	v_rcp_f32_e32 v21, v21
	v_rcp_f32_e32 v22, v22
	v_rcp_f32_e32 v23, v23
	v_lshlrev_b32_e32 v24, 16, v212
	v_and_b32_e32 v25, 0xffff0000, v212
	v_lshlrev_b32_e32 v26, 16, v213
	v_and_b32_e32 v27, 0xffff0000, v213
	v_lshlrev_b32_e32 v28, 16, v214
	v_and_b32_e32 v29, 0xffff0000, v214
	v_lshlrev_b32_e32 v30, 16, v215
	v_and_b32_e32 v31, 0xffff0000, v215
	v_mul_f32_e32 v24, v24, v16
	v_mul_f32_e32 v25, v25, v17
	v_mul_f32_e32 v26, v26, v18
	v_mul_f32_e32 v27, v27, v19
	v_mul_f32_e32 v28, v28, v20
	v_mul_f32_e32 v29, v29, v21
	v_mul_f32_e32 v30, v30, v22
	v_mul_f32_e32 v31, v31, v23
	ds_write_b128 v232, v[24:27] offset:49152
	ds_write_b128 v232, v[28:31] offset:49168
	s_waitcnt lgkmcnt(0)
	s_barrier
	s_add_u32 s13, s4, 0x100
	s_cmp_lt_u32 s13, s5
	s_cselect_b32 s18, s13, s4
	s_sub_u32 s16, s18, 0x400
	s_lshr_b32 s17, s16, 3
	s_lshl_b32 s17, s17, 8
	s_add_u32 s17, s17, 0x8000
	s_and_b32 s16, s16, 7
	s_lshr_b32 s14, s18, 7
	s_lshl_b32 s14, s14, 12
	s_and_b32 s15, s18, 0x7f
	s_cmp_lt_u32 s18, 0x400
	s_cselect_b32 s14, s14, s17
	s_cselect_b32 s15, s15, s16
	s_movk_i32 s16, 0x100
	s_cselect_b32 s19, 0x1000, s16
	s_lshl_b32 s15, s15, 5
	s_add_u32 s14, s14, s15
	s_sub_u32 s16, s14, 15
	s_mul_i32 s16, s16, 0x1440
	s_ashr_i32 s17, s16, 31
	s_add_u32 s6, s50, s16
	s_addc_u32 s7, s51, s17
	s_add_u32 s6, s6, 0x5cbd000
	s_addc_u32 s7, s7, 0
	global_load_dwordx4 v[188:191], v228, s[6:7]
	global_load_dwordx4 v[192:195], v228, s[6:7] offset:512
	global_load_dwordx4 v[196:199], v229, s[6:7]
	global_load_dwordx4 v[200:203], v229, s[6:7] offset:512
	global_load_dwordx4 v[204:207], v230, s[6:7]
	global_load_dwordx4 v[208:211], v230, s[6:7] offset:512
	global_load_dwordx4 v[212:215], v231, s[6:7]
	global_load_dwordx4 v[216:219], v231, s[6:7] offset:512
	ds_read2st64_b32 v[48:49], v237 offset0:0 offset1:4
	ds_read2st64_b32 v[50:51], v237 offset0:8 offset1:12
	ds_read2st64_b32 v[52:53], v237 offset0:16 offset1:20
	ds_read2st64_b32 v[54:55], v237 offset0:24 offset1:28
	ds_read2st64_b32 v[56:57], v237 offset0:32 offset1:36
	ds_read2st64_b32 v[58:59], v237 offset0:40 offset1:44
	ds_read2st64_b32 v[60:61], v237 offset0:48 offset1:52
	ds_read2st64_b32 v[62:63], v237 offset0:56 offset1:60
	ds_read2st64_b32 v[64:65], v237 offset0:64 offset1:68
	ds_read2st64_b32 v[66:67], v237 offset0:72 offset1:76
	ds_read2st64_b32 v[68:69], v237 offset0:80 offset1:84
	ds_read2st64_b32 v[70:71], v237 offset0:88 offset1:92
	s_waitcnt lgkmcnt(11)
	v_fma_f32 v0, v96, v48, v127
	v_fmac_f32_e32 v0, v97, v49
	v_fma_f32 v1, v96, v49, v127
	ds_read2st64_b32 v[48:49], v237 offset0:96 offset1:100
	s_waitcnt lgkmcnt(11)
	v_fmac_f32_e32 v0, v98, v50
	v_fmac_f32_e32 v1, v97, v50
	v_fma_f32 v2, v96, v50, v127
	v_fmac_f32_e32 v0, v99, v51
	v_fmac_f32_e32 v1, v98, v51
	v_fmac_f32_e32 v2, v97, v51
	v_fma_f32 v3, v96, v51, v127
	ds_read2st64_b32 v[50:51], v237 offset0:104 offset1:108
	s_waitcnt lgkmcnt(11)
	v_fmac_f32_e32 v0, v100, v52
	v_fmac_f32_e32 v1, v99, v52
	v_fmac_f32_e32 v2, v98, v52
	v_fmac_f32_e32 v3, v97, v52
	v_fma_f32 v4, v96, v52, v127
	v_fmac_f32_e32 v0, v101, v53
	v_fmac_f32_e32 v1, v100, v53
	v_fmac_f32_e32 v2, v99, v53
	v_fmac_f32_e32 v3, v98, v53
	v_fmac_f32_e32 v4, v97, v53
	v_fma_f32 v5, v96, v53, v127
	ds_read2st64_b32 v[52:53], v237 offset0:112 offset1:116
	s_waitcnt lgkmcnt(11)
	v_fmac_f32_e32 v0, v102, v54
	v_fmac_f32_e32 v1, v101, v54
	v_fmac_f32_e32 v2, v100, v54
	v_fmac_f32_e32 v3, v99, v54
	v_fmac_f32_e32 v4, v98, v54
	v_fmac_f32_e32 v5, v97, v54
	v_fma_f32 v6, v96, v54, v127
	v_fmac_f32_e32 v0, v103, v55
	v_fmac_f32_e32 v1, v102, v55
	v_fmac_f32_e32 v2, v101, v55
	v_fmac_f32_e32 v3, v100, v55
	v_fmac_f32_e32 v4, v99, v55
	v_fmac_f32_e32 v5, v98, v55
	v_fmac_f32_e32 v6, v97, v55
	v_fma_f32 v7, v96, v55, v127
	ds_read2st64_b32 v[54:55], v237 offset0:120 offset1:124
	s_waitcnt lgkmcnt(11)
	v_fmac_f32_e32 v0, v104, v56
	v_fmac_f32_e32 v1, v103, v56
	v_fmac_f32_e32 v2, v102, v56
	v_fmac_f32_e32 v3, v101, v56
	v_fmac_f32_e32 v4, v100, v56
	v_fmac_f32_e32 v5, v99, v56
	v_fmac_f32_e32 v6, v98, v56
	v_fmac_f32_e32 v7, v97, v56
	v_fma_f32 v8, v96, v56, v127
	v_fmac_f32_e32 v0, v105, v57
	v_fmac_f32_e32 v1, v104, v57
	v_fmac_f32_e32 v2, v103, v57
	v_fmac_f32_e32 v3, v102, v57
	v_fmac_f32_e32 v4, v101, v57
	v_fmac_f32_e32 v5, v100, v57
	v_fmac_f32_e32 v6, v99, v57
	v_fmac_f32_e32 v7, v98, v57
	v_fmac_f32_e32 v8, v97, v57
	v_fma_f32 v9, v96, v57, v127
	ds_read2st64_b32 v[56:57], v237 offset0:128 offset1:132
	s_waitcnt lgkmcnt(11)
	v_fmac_f32_e32 v0, v106, v58
	v_fmac_f32_e32 v1, v105, v58
	v_fmac_f32_e32 v2, v104, v58
	v_fmac_f32_e32 v3, v103, v58
	v_fmac_f32_e32 v4, v102, v58
	v_fmac_f32_e32 v5, v101, v58
	v_fmac_f32_e32 v6, v100, v58
	v_fmac_f32_e32 v7, v99, v58
	v_fmac_f32_e32 v8, v98, v58
	v_fmac_f32_e32 v9, v97, v58
	v_fma_f32 v10, v96, v58, v127
	v_fmac_f32_e32 v0, v107, v59
	v_fmac_f32_e32 v1, v106, v59
	v_fmac_f32_e32 v2, v105, v59
	v_fmac_f32_e32 v3, v104, v59
	v_fmac_f32_e32 v4, v103, v59
	v_fmac_f32_e32 v5, v102, v59
	v_fmac_f32_e32 v6, v101, v59
	v_fmac_f32_e32 v7, v100, v59
	v_fmac_f32_e32 v8, v99, v59
	v_fmac_f32_e32 v9, v98, v59
	v_fmac_f32_e32 v10, v97, v59
	v_fma_f32 v11, v96, v59, v127
	ds_read2st64_b32 v[58:59], v237 offset0:136 offset1:140
	s_waitcnt lgkmcnt(11)
	v_fmac_f32_e32 v0, v108, v60
	v_fmac_f32_e32 v1, v107, v60
	v_fmac_f32_e32 v2, v106, v60
	v_fmac_f32_e32 v3, v105, v60
	v_fmac_f32_e32 v4, v104, v60
	v_fmac_f32_e32 v5, v103, v60
	v_fmac_f32_e32 v6, v102, v60
	v_fmac_f32_e32 v7, v101, v60
	v_fmac_f32_e32 v8, v100, v60
	v_fmac_f32_e32 v9, v99, v60
	v_fmac_f32_e32 v10, v98, v60
	v_fmac_f32_e32 v11, v97, v60
	v_fma_f32 v12, v96, v60, v127
	v_fmac_f32_e32 v0, v109, v61
	v_fmac_f32_e32 v1, v108, v61
	v_fmac_f32_e32 v2, v107, v61
	v_fmac_f32_e32 v3, v106, v61
	v_fmac_f32_e32 v4, v105, v61
	v_fmac_f32_e32 v5, v104, v61
	v_fmac_f32_e32 v6, v103, v61
	v_fmac_f32_e32 v7, v102, v61
	v_fmac_f32_e32 v8, v101, v61
	v_fmac_f32_e32 v9, v100, v61
	v_fmac_f32_e32 v10, v99, v61
	v_fmac_f32_e32 v11, v98, v61
	v_fmac_f32_e32 v12, v97, v61
	v_fma_f32 v13, v96, v61, v127
	ds_read2st64_b32 v[60:61], v237 offset0:144 offset1:148
	s_waitcnt lgkmcnt(11)
	v_fmac_f32_e32 v0, v110, v62
	v_fmac_f32_e32 v1, v109, v62
	v_fmac_f32_e32 v2, v108, v62
	v_fmac_f32_e32 v3, v107, v62
	v_fmac_f32_e32 v4, v106, v62
	v_fmac_f32_e32 v5, v105, v62
	v_fmac_f32_e32 v6, v104, v62
	v_fmac_f32_e32 v7, v103, v62
	v_fmac_f32_e32 v8, v102, v62
	v_fmac_f32_e32 v9, v101, v62
	v_fmac_f32_e32 v10, v100, v62
	v_fmac_f32_e32 v11, v99, v62
	v_fmac_f32_e32 v12, v98, v62
	v_fmac_f32_e32 v13, v97, v62
	v_fma_f32 v14, v96, v62, v127
	v_fmac_f32_e32 v0, v111, v63
	v_fmac_f32_e32 v1, v110, v63
	v_fmac_f32_e32 v2, v109, v63
	v_fmac_f32_e32 v3, v108, v63
	v_fmac_f32_e32 v4, v107, v63
	v_fmac_f32_e32 v5, v106, v63
	v_fmac_f32_e32 v6, v105, v63
	v_fmac_f32_e32 v7, v104, v63
	v_fmac_f32_e32 v8, v103, v63
	v_fmac_f32_e32 v9, v102, v63
	v_fmac_f32_e32 v10, v101, v63
	v_fmac_f32_e32 v11, v100, v63
	v_fmac_f32_e32 v12, v99, v63
	v_fmac_f32_e32 v13, v98, v63
	v_fmac_f32_e32 v14, v97, v63
	v_fma_f32 v15, v96, v63, v127
	ds_read2st64_b32 v[62:63], v237 offset0:152 offset1:156
	s_waitcnt lgkmcnt(11)
	v_fmac_f32_e32 v0, v112, v64
	v_fmac_f32_e32 v1, v111, v64
	v_fmac_f32_e32 v2, v110, v64
	v_fmac_f32_e32 v3, v109, v64
	v_fmac_f32_e32 v4, v108, v64
	v_fmac_f32_e32 v5, v107, v64
	v_fmac_f32_e32 v6, v106, v64
	v_fmac_f32_e32 v7, v105, v64
	v_fmac_f32_e32 v8, v104, v64
	v_fmac_f32_e32 v9, v103, v64
	v_fmac_f32_e32 v10, v102, v64
	v_fmac_f32_e32 v11, v101, v64
	v_fmac_f32_e32 v12, v100, v64
	v_fmac_f32_e32 v13, v99, v64
	v_fmac_f32_e32 v14, v98, v64
	v_fmac_f32_e32 v15, v97, v64
	v_fmac_f32_e32 v0, v113, v65
	v_fmac_f32_e32 v1, v112, v65
	v_fmac_f32_e32 v2, v111, v65
	v_fmac_f32_e32 v3, v110, v65
	v_fmac_f32_e32 v4, v109, v65
	v_fmac_f32_e32 v5, v108, v65
	v_fmac_f32_e32 v6, v107, v65
	v_fmac_f32_e32 v7, v106, v65
	v_fmac_f32_e32 v8, v105, v65
	v_fmac_f32_e32 v9, v104, v65
	v_fmac_f32_e32 v10, v103, v65
	v_fmac_f32_e32 v11, v102, v65
	v_fmac_f32_e32 v12, v101, v65
	v_fmac_f32_e32 v13, v100, v65
	v_fmac_f32_e32 v14, v99, v65
	v_fmac_f32_e32 v15, v98, v65
	ds_read2st64_b32 v[64:65], v237 offset0:160 offset1:164
	s_waitcnt lgkmcnt(11)
	v_fmac_f32_e32 v0, v114, v66
	v_fmac_f32_e32 v1, v113, v66
	v_fmac_f32_e32 v2, v112, v66
	v_fmac_f32_e32 v3, v111, v66
	v_fmac_f32_e32 v4, v110, v66
	v_fmac_f32_e32 v5, v109, v66
	v_fmac_f32_e32 v6, v108, v66
	v_fmac_f32_e32 v7, v107, v66
	v_fmac_f32_e32 v8, v106, v66
	v_fmac_f32_e32 v9, v105, v66
	v_fmac_f32_e32 v10, v104, v66
	v_fmac_f32_e32 v11, v103, v66
	v_fmac_f32_e32 v12, v102, v66
	v_fmac_f32_e32 v13, v101, v66
	v_fmac_f32_e32 v14, v100, v66
	v_fmac_f32_e32 v15, v99, v66
	v_fmac_f32_e32 v0, v115, v67
	v_fmac_f32_e32 v1, v114, v67
	v_fmac_f32_e32 v2, v113, v67
	v_fmac_f32_e32 v3, v112, v67
	v_fmac_f32_e32 v4, v111, v67
	v_fmac_f32_e32 v5, v110, v67
	v_fmac_f32_e32 v6, v109, v67
	v_fmac_f32_e32 v7, v108, v67
	v_fmac_f32_e32 v8, v107, v67
	v_fmac_f32_e32 v9, v106, v67
	v_fmac_f32_e32 v10, v105, v67
	v_fmac_f32_e32 v11, v104, v67
	v_fmac_f32_e32 v12, v103, v67
	v_fmac_f32_e32 v13, v102, v67
	v_fmac_f32_e32 v14, v101, v67
	v_fmac_f32_e32 v15, v100, v67
	ds_read2st64_b32 v[66:67], v237 offset0:168 offset1:172
	s_waitcnt lgkmcnt(11)
	v_fmac_f32_e32 v0, v116, v68
	v_fmac_f32_e32 v1, v115, v68
	v_fmac_f32_e32 v2, v114, v68
	v_fmac_f32_e32 v3, v113, v68
	v_fmac_f32_e32 v4, v112, v68
	v_fmac_f32_e32 v5, v111, v68
	v_fmac_f32_e32 v6, v110, v68
	v_fmac_f32_e32 v7, v109, v68
	v_fmac_f32_e32 v8, v108, v68
	v_fmac_f32_e32 v9, v107, v68
	v_fmac_f32_e32 v10, v106, v68
	v_fmac_f32_e32 v11, v105, v68
	v_fmac_f32_e32 v12, v104, v68
	v_fmac_f32_e32 v13, v103, v68
	v_fmac_f32_e32 v14, v102, v68
	v_fmac_f32_e32 v15, v101, v68
	v_fmac_f32_e32 v0, v117, v69
	v_fmac_f32_e32 v1, v116, v69
	v_fmac_f32_e32 v2, v115, v69
	v_fmac_f32_e32 v3, v114, v69
	v_fmac_f32_e32 v4, v113, v69
	v_fmac_f32_e32 v5, v112, v69
	v_fmac_f32_e32 v6, v111, v69
	v_fmac_f32_e32 v7, v110, v69
	v_fmac_f32_e32 v8, v109, v69
	v_fmac_f32_e32 v9, v108, v69
	v_fmac_f32_e32 v10, v107, v69
	v_fmac_f32_e32 v11, v106, v69
	v_fmac_f32_e32 v12, v105, v69
	v_fmac_f32_e32 v13, v104, v69
	v_fmac_f32_e32 v14, v103, v69
	v_fmac_f32_e32 v15, v102, v69
	ds_read2st64_b32 v[68:69], v237 offset0:176 offset1:180
	s_waitcnt lgkmcnt(11)
	v_fmac_f32_e32 v0, v118, v70
	v_fmac_f32_e32 v1, v117, v70
	v_fmac_f32_e32 v2, v116, v70
	v_fmac_f32_e32 v3, v115, v70
	v_fmac_f32_e32 v4, v114, v70
	v_fmac_f32_e32 v5, v113, v70
	v_fmac_f32_e32 v6, v112, v70
	v_fmac_f32_e32 v7, v111, v70
	v_fmac_f32_e32 v8, v110, v70
	v_fmac_f32_e32 v9, v109, v70
	v_fmac_f32_e32 v10, v108, v70
	v_fmac_f32_e32 v11, v107, v70
	v_fmac_f32_e32 v12, v106, v70
	v_fmac_f32_e32 v13, v105, v70
	v_fmac_f32_e32 v14, v104, v70
	v_fmac_f32_e32 v15, v103, v70
	v_fmac_f32_e32 v0, v119, v71
	v_fmac_f32_e32 v1, v118, v71
	v_fmac_f32_e32 v2, v117, v71
	v_fmac_f32_e32 v3, v116, v71
	v_fmac_f32_e32 v4, v115, v71
	v_fmac_f32_e32 v5, v114, v71
	v_fmac_f32_e32 v6, v113, v71
	v_fmac_f32_e32 v7, v112, v71
	v_fmac_f32_e32 v8, v111, v71
	v_fmac_f32_e32 v9, v110, v71
	v_fmac_f32_e32 v10, v109, v71
	v_fmac_f32_e32 v11, v108, v71
	v_fmac_f32_e32 v12, v107, v71
	v_fmac_f32_e32 v13, v106, v71
	v_fmac_f32_e32 v14, v105, v71
	v_fmac_f32_e32 v15, v104, v71
	s_waitcnt lgkmcnt(10)
	v_fmac_f32_e32 v0, v120, v48
	v_fmac_f32_e32 v1, v119, v48
	v_fmac_f32_e32 v2, v118, v48
	v_fmac_f32_e32 v3, v117, v48
	v_fmac_f32_e32 v4, v116, v48
	v_fmac_f32_e32 v5, v115, v48
	v_fmac_f32_e32 v6, v114, v48
	v_fmac_f32_e32 v7, v113, v48
	v_fmac_f32_e32 v8, v112, v48
	v_fmac_f32_e32 v9, v111, v48
	v_fmac_f32_e32 v10, v110, v48
	v_fmac_f32_e32 v11, v109, v48
	v_fmac_f32_e32 v12, v108, v48
	v_fmac_f32_e32 v13, v107, v48
	v_fmac_f32_e32 v14, v106, v48
	v_fmac_f32_e32 v15, v105, v48
	v_fmac_f32_e32 v0, v121, v49
	v_fmac_f32_e32 v1, v120, v49
	v_fmac_f32_e32 v2, v119, v49
	v_fmac_f32_e32 v3, v118, v49
	v_fmac_f32_e32 v4, v117, v49
	v_fmac_f32_e32 v5, v116, v49
	v_fmac_f32_e32 v6, v115, v49
	v_fmac_f32_e32 v7, v114, v49
	v_fmac_f32_e32 v8, v113, v49
	v_fmac_f32_e32 v9, v112, v49
	v_fmac_f32_e32 v10, v111, v49
	v_fmac_f32_e32 v11, v110, v49
	v_fmac_f32_e32 v12, v109, v49
	v_fmac_f32_e32 v13, v108, v49
	v_fmac_f32_e32 v14, v107, v49
	v_fmac_f32_e32 v15, v106, v49
	s_waitcnt lgkmcnt(9)
	v_fmac_f32_e32 v0, v122, v50
	v_fmac_f32_e32 v1, v121, v50
	v_fmac_f32_e32 v2, v120, v50
	v_fmac_f32_e32 v3, v119, v50
	v_fmac_f32_e32 v4, v118, v50
	v_fmac_f32_e32 v5, v117, v50
	v_fmac_f32_e32 v6, v116, v50
	v_fmac_f32_e32 v7, v115, v50
	v_fmac_f32_e32 v8, v114, v50
	v_fmac_f32_e32 v9, v113, v50
	v_fmac_f32_e32 v10, v112, v50
	v_fmac_f32_e32 v11, v111, v50
	v_fmac_f32_e32 v12, v110, v50
	v_fmac_f32_e32 v13, v109, v50
	v_fmac_f32_e32 v14, v108, v50
	v_fmac_f32_e32 v15, v107, v50
	v_fmac_f32_e32 v0, v123, v51
	v_fmac_f32_e32 v1, v122, v51
	v_fmac_f32_e32 v2, v121, v51
	v_fmac_f32_e32 v3, v120, v51
	v_fmac_f32_e32 v4, v119, v51
	v_fmac_f32_e32 v5, v118, v51
	v_fmac_f32_e32 v6, v117, v51
	v_fmac_f32_e32 v7, v116, v51
	v_fmac_f32_e32 v8, v115, v51
	v_fmac_f32_e32 v9, v114, v51
	v_fmac_f32_e32 v10, v113, v51
	v_fmac_f32_e32 v11, v112, v51
	v_fmac_f32_e32 v12, v111, v51
	v_fmac_f32_e32 v13, v110, v51
	v_fmac_f32_e32 v14, v109, v51
	v_fmac_f32_e32 v15, v108, v51
	s_waitcnt lgkmcnt(8)
	v_fmac_f32_e32 v0, v124, v52
	v_fmac_f32_e32 v1, v123, v52
	v_fmac_f32_e32 v2, v122, v52
	v_fmac_f32_e32 v3, v121, v52
	v_fmac_f32_e32 v4, v120, v52
	v_fmac_f32_e32 v5, v119, v52
	v_fmac_f32_e32 v6, v118, v52
	v_fmac_f32_e32 v7, v117, v52
	v_fmac_f32_e32 v8, v116, v52
	v_fmac_f32_e32 v9, v115, v52
	v_fmac_f32_e32 v10, v114, v52
	v_fmac_f32_e32 v11, v113, v52
	v_fmac_f32_e32 v12, v112, v52
	v_fmac_f32_e32 v13, v111, v52
	v_fmac_f32_e32 v14, v110, v52
	v_fmac_f32_e32 v15, v109, v52
	v_fmac_f32_e32 v0, v125, v53
	v_fmac_f32_e32 v1, v124, v53
	v_fmac_f32_e32 v2, v123, v53
	v_fmac_f32_e32 v3, v122, v53
	v_fmac_f32_e32 v4, v121, v53
	v_fmac_f32_e32 v5, v120, v53
	v_fmac_f32_e32 v6, v119, v53
	v_fmac_f32_e32 v7, v118, v53
	v_fmac_f32_e32 v8, v117, v53
	v_fmac_f32_e32 v9, v116, v53
	v_fmac_f32_e32 v10, v115, v53
	v_fmac_f32_e32 v11, v114, v53
	v_fmac_f32_e32 v12, v113, v53
	v_fmac_f32_e32 v13, v112, v53
	v_fmac_f32_e32 v14, v111, v53
	v_fmac_f32_e32 v15, v110, v53
	s_waitcnt lgkmcnt(7)
	v_fmac_f32_e32 v0, v126, v54
	v_fmac_f32_e32 v1, v125, v54
	v_fmac_f32_e32 v2, v124, v54
	v_fmac_f32_e32 v3, v123, v54
	v_fmac_f32_e32 v4, v122, v54
	v_fmac_f32_e32 v5, v121, v54
	v_fmac_f32_e32 v6, v120, v54
	v_fmac_f32_e32 v7, v119, v54
	v_fmac_f32_e32 v8, v118, v54
	v_fmac_f32_e32 v9, v117, v54
	v_fmac_f32_e32 v10, v116, v54
	v_fmac_f32_e32 v11, v115, v54
	v_fmac_f32_e32 v12, v114, v54
	v_fmac_f32_e32 v13, v113, v54
	v_fmac_f32_e32 v14, v112, v54
	v_fmac_f32_e32 v15, v111, v54
	v_fmac_f32_e32 v1, v126, v55
	v_fmac_f32_e32 v2, v125, v55
	v_fmac_f32_e32 v3, v124, v55
	v_fmac_f32_e32 v4, v123, v55
	v_fmac_f32_e32 v5, v122, v55
	v_fmac_f32_e32 v6, v121, v55
	v_fmac_f32_e32 v7, v120, v55
	v_fmac_f32_e32 v8, v119, v55
	v_fmac_f32_e32 v9, v118, v55
	v_fmac_f32_e32 v10, v117, v55
	v_fmac_f32_e32 v11, v116, v55
	v_fmac_f32_e32 v12, v115, v55
	v_fmac_f32_e32 v13, v114, v55
	v_fmac_f32_e32 v14, v113, v55
	v_fmac_f32_e32 v15, v112, v55
	s_waitcnt lgkmcnt(6)
	v_fmac_f32_e32 v2, v126, v56
	v_fmac_f32_e32 v3, v125, v56
	v_fmac_f32_e32 v4, v124, v56
	v_fmac_f32_e32 v5, v123, v56
	v_fmac_f32_e32 v6, v122, v56
	v_fmac_f32_e32 v7, v121, v56
	v_fmac_f32_e32 v8, v120, v56
	v_fmac_f32_e32 v9, v119, v56
	v_fmac_f32_e32 v10, v118, v56
	v_fmac_f32_e32 v11, v117, v56
	v_fmac_f32_e32 v12, v116, v56
	v_fmac_f32_e32 v13, v115, v56
	v_fmac_f32_e32 v14, v114, v56
	v_fmac_f32_e32 v15, v113, v56
	v_fmac_f32_e32 v3, v126, v57
	v_fmac_f32_e32 v4, v125, v57
	v_fmac_f32_e32 v5, v124, v57
	v_fmac_f32_e32 v6, v123, v57
	v_fmac_f32_e32 v7, v122, v57
	v_fmac_f32_e32 v8, v121, v57
	v_fmac_f32_e32 v9, v120, v57
	v_fmac_f32_e32 v10, v119, v57
	v_fmac_f32_e32 v11, v118, v57
	v_fmac_f32_e32 v12, v117, v57
	v_fmac_f32_e32 v13, v116, v57
	v_fmac_f32_e32 v14, v115, v57
	v_fmac_f32_e32 v15, v114, v57
	s_waitcnt lgkmcnt(5)
	v_fmac_f32_e32 v4, v126, v58
	v_fmac_f32_e32 v5, v125, v58
	v_fmac_f32_e32 v6, v124, v58
	v_fmac_f32_e32 v7, v123, v58
	v_fmac_f32_e32 v8, v122, v58
	v_fmac_f32_e32 v9, v121, v58
	v_fmac_f32_e32 v10, v120, v58
	v_fmac_f32_e32 v11, v119, v58
	v_fmac_f32_e32 v12, v118, v58
	v_fmac_f32_e32 v13, v117, v58
	v_fmac_f32_e32 v14, v116, v58
	v_fmac_f32_e32 v15, v115, v58
	v_fmac_f32_e32 v5, v126, v59
	v_fmac_f32_e32 v6, v125, v59
	v_fmac_f32_e32 v7, v124, v59
	v_fmac_f32_e32 v8, v123, v59
	v_fmac_f32_e32 v9, v122, v59
	v_fmac_f32_e32 v10, v121, v59
	v_fmac_f32_e32 v11, v120, v59
	v_fmac_f32_e32 v12, v119, v59
	v_fmac_f32_e32 v13, v118, v59
	v_fmac_f32_e32 v14, v117, v59
	v_fmac_f32_e32 v15, v116, v59
	s_waitcnt lgkmcnt(4)
	v_fmac_f32_e32 v6, v126, v60
	v_fmac_f32_e32 v7, v125, v60
	v_fmac_f32_e32 v8, v124, v60
	v_fmac_f32_e32 v9, v123, v60
	v_fmac_f32_e32 v10, v122, v60
	v_fmac_f32_e32 v11, v121, v60
	v_fmac_f32_e32 v12, v120, v60
	v_fmac_f32_e32 v13, v119, v60
	v_fmac_f32_e32 v14, v118, v60
	v_fmac_f32_e32 v15, v117, v60
	v_fmac_f32_e32 v7, v126, v61
	v_fmac_f32_e32 v8, v125, v61
	v_fmac_f32_e32 v9, v124, v61
	v_fmac_f32_e32 v10, v123, v61
	v_fmac_f32_e32 v11, v122, v61
	v_fmac_f32_e32 v12, v121, v61
	v_fmac_f32_e32 v13, v120, v61
	v_fmac_f32_e32 v14, v119, v61
	v_fmac_f32_e32 v15, v118, v61
	s_waitcnt lgkmcnt(3)
	v_fmac_f32_e32 v8, v126, v62
	v_fmac_f32_e32 v9, v125, v62
	v_fmac_f32_e32 v10, v124, v62
	v_fmac_f32_e32 v11, v123, v62
	v_fmac_f32_e32 v12, v122, v62
	v_fmac_f32_e32 v13, v121, v62
	v_fmac_f32_e32 v14, v120, v62
	v_fmac_f32_e32 v15, v119, v62
	v_fmac_f32_e32 v9, v126, v63
	v_fmac_f32_e32 v10, v125, v63
	v_fmac_f32_e32 v11, v124, v63
	v_fmac_f32_e32 v12, v123, v63
	v_fmac_f32_e32 v13, v122, v63
	v_fmac_f32_e32 v14, v121, v63
	v_fmac_f32_e32 v15, v120, v63
	s_waitcnt lgkmcnt(2)
	v_fmac_f32_e32 v10, v126, v64
	v_fmac_f32_e32 v11, v125, v64
	v_fmac_f32_e32 v12, v124, v64
	v_fmac_f32_e32 v13, v123, v64
	v_fmac_f32_e32 v14, v122, v64
	v_fmac_f32_e32 v15, v121, v64
	v_fmac_f32_e32 v11, v126, v65
	v_fmac_f32_e32 v12, v125, v65
	v_fmac_f32_e32 v13, v124, v65
	v_fmac_f32_e32 v14, v123, v65
	v_fmac_f32_e32 v15, v122, v65
	s_waitcnt lgkmcnt(1)
	v_fmac_f32_e32 v12, v126, v66
	v_fmac_f32_e32 v13, v125, v66
	v_fmac_f32_e32 v14, v124, v66
	v_fmac_f32_e32 v15, v123, v66
	v_fmac_f32_e32 v13, v126, v67
	v_fmac_f32_e32 v14, v125, v67
	v_fmac_f32_e32 v15, v124, v67
	s_waitcnt lgkmcnt(0)
	v_fmac_f32_e32 v14, v126, v68
	v_fmac_f32_e32 v15, v125, v68
	v_fmac_f32_e32 v15, v126, v69
	ds_write2st64_b32 v238, v0, v1 offset0:0 offset1:4
	ds_write2st64_b32 v238, v2, v3 offset0:8 offset1:12
	ds_write2st64_b32 v238, v4, v5 offset0:16 offset1:20
	ds_write2st64_b32 v238, v6, v7 offset0:24 offset1:28
	ds_write2st64_b32 v238, v8, v9 offset0:32 offset1:36
	ds_write2st64_b32 v238, v10, v11 offset0:40 offset1:44
	ds_write2st64_b32 v238, v12, v13 offset0:48 offset1:52
	ds_write2st64_b32 v238, v14, v15 offset0:56 offset1:60
	s_waitcnt lgkmcnt(0)
	s_barrier
	ds_read_b128 v[0:3], v239 offset:0
	ds_read_b128 v[4:7], v239 offset:1024
	ds_read_b128 v[8:11], v239 offset:2048
	ds_read_b128 v[12:15], v239 offset:3072
	s_waitcnt lgkmcnt(0)
	v_add_f32_e32 v16, v0, v1
	v_add_f32_e32 v17, v4, v5
	v_add_f32_e32 v18, v8, v9
	v_add_f32_e32 v19, v12, v13
	v_add_f32_e32 v20, v2, v3
	v_add_f32_e32 v21, v6, v7
	v_add_f32_e32 v22, v10, v11
	v_add_f32_e32 v23, v14, v15
	v_add_f32_e32 v16, v16, v20
	v_add_f32_e32 v17, v17, v21
	v_add_f32_e32 v18, v18, v22
	v_add_f32_e32 v19, v19, v23
	v_add_f32_dpp v16, v16, v16 quad_perm:[1,0,3,2] row_mask:0xf bank_mask:0xf
	v_add_f32_dpp v17, v17, v17 quad_perm:[1,0,3,2] row_mask:0xf bank_mask:0xf
	v_add_f32_dpp v18, v18, v18 quad_perm:[1,0,3,2] row_mask:0xf bank_mask:0xf
	v_add_f32_dpp v19, v19, v19 quad_perm:[1,0,3,2] row_mask:0xf bank_mask:0xf
	v_add_f32_dpp v16, v16, v16 quad_perm:[2,3,0,1] row_mask:0xf bank_mask:0xf
	v_add_f32_dpp v17, v17, v17 quad_perm:[2,3,0,1] row_mask:0xf bank_mask:0xf
	v_add_f32_dpp v18, v18, v18 quad_perm:[2,3,0,1] row_mask:0xf bank_mask:0xf
	v_add_f32_dpp v19, v19, v19 quad_perm:[2,3,0,1] row_mask:0xf bank_mask:0xf
	v_add_f32_dpp v16, v16, v16 row_half_mirror row_mask:0xf bank_mask:0xf
	v_add_f32_dpp v17, v17, v17 row_half_mirror row_mask:0xf bank_mask:0xf
	v_add_f32_dpp v18, v18, v18 row_half_mirror row_mask:0xf bank_mask:0xf
	v_add_f32_dpp v19, v19, v19 row_half_mirror row_mask:0xf bank_mask:0xf
	v_add_f32_dpp v16, v16, v16 row_mirror row_mask:0xf bank_mask:0xf
	v_add_f32_dpp v17, v17, v17 row_mirror row_mask:0xf bank_mask:0xf
	v_add_f32_dpp v18, v18, v18 row_mirror row_mask:0xf bank_mask:0xf
	v_add_f32_dpp v19, v19, v19 row_mirror row_mask:0xf bank_mask:0xf
	v_mov_b32_e32 v20, v16
	v_mov_b32_e32 v21, v17
	v_mov_b32_e32 v22, v18
	v_mov_b32_e32 v23, v19
	v_permlane16_swap_b32_e32 v16, v20
	v_permlane16_swap_b32_e32 v17, v21
	v_permlane16_swap_b32_e32 v18, v22
	v_permlane16_swap_b32_e32 v19, v23
	v_add_f32_e32 v16, v16, v20
	v_add_f32_e32 v17, v17, v21
	v_add_f32_e32 v18, v18, v22
	v_add_f32_e32 v19, v19, v23
	v_mov_b32_e32 v20, v16
	v_mov_b32_e32 v21, v17
	v_mov_b32_e32 v22, v18
	v_mov_b32_e32 v23, v19
	v_permlane32_swap_b32_e32 v16, v20
	v_permlane32_swap_b32_e32 v17, v21
	v_permlane32_swap_b32_e32 v18, v22
	v_permlane32_swap_b32_e32 v19, v23
	v_add_f32_e32 v16, v16, v20
	v_add_f32_e32 v17, v17, v21
	v_add_f32_e32 v18, v18, v22
	v_add_f32_e32 v19, v19, v23
	v_mul_f32_e32 v16, 0x3b800000, v16
	v_mul_f32_e32 v17, 0x3b800000, v17
	v_mul_f32_e32 v18, 0x3b800000, v18
	v_mul_f32_e32 v19, 0x3b800000, v19
	v_sub_f32_e32 v0, v0, v16
	v_sub_f32_e32 v4, v4, v17
	v_sub_f32_e32 v8, v8, v18
	v_sub_f32_e32 v12, v12, v19
	v_sub_f32_e32 v1, v1, v16
	v_sub_f32_e32 v5, v5, v17
	v_sub_f32_e32 v9, v9, v18
	v_sub_f32_e32 v13, v13, v19
	v_sub_f32_e32 v2, v2, v16
	v_sub_f32_e32 v6, v6, v17
	v_sub_f32_e32 v10, v10, v18
	v_sub_f32_e32 v14, v14, v19
	v_sub_f32_e32 v3, v3, v16
	v_sub_f32_e32 v7, v7, v17
	v_sub_f32_e32 v11, v11, v18
	v_sub_f32_e32 v15, v15, v19
	v_mul_f32_e32 v20, v0, v0
	v_mul_f32_e32 v21, v4, v4
	v_mul_f32_e32 v22, v8, v8
	v_mul_f32_e32 v23, v12, v12
	v_fmac_f32_e32 v20, v1, v1
	v_fmac_f32_e32 v21, v5, v5
	v_fmac_f32_e32 v22, v9, v9
	v_fmac_f32_e32 v23, v13, v13
	v_fmac_f32_e32 v20, v2, v2
	v_fmac_f32_e32 v21, v6, v6
	v_fmac_f32_e32 v22, v10, v10
	v_fmac_f32_e32 v23, v14, v14
	v_fmac_f32_e32 v20, v3, v3
	v_fmac_f32_e32 v21, v7, v7
	v_fmac_f32_e32 v22, v11, v11
	v_fmac_f32_e32 v23, v15, v15
	v_add_f32_dpp v20, v20, v20 quad_perm:[1,0,3,2] row_mask:0xf bank_mask:0xf
	v_add_f32_dpp v21, v21, v21 quad_perm:[1,0,3,2] row_mask:0xf bank_mask:0xf
	v_add_f32_dpp v22, v22, v22 quad_perm:[1,0,3,2] row_mask:0xf bank_mask:0xf
	v_add_f32_dpp v23, v23, v23 quad_perm:[1,0,3,2] row_mask:0xf bank_mask:0xf
	v_add_f32_dpp v20, v20, v20 quad_perm:[2,3,0,1] row_mask:0xf bank_mask:0xf
	v_add_f32_dpp v21, v21, v21 quad_perm:[2,3,0,1] row_mask:0xf bank_mask:0xf
	v_add_f32_dpp v22, v22, v22 quad_perm:[2,3,0,1] row_mask:0xf bank_mask:0xf
	v_add_f32_dpp v23, v23, v23 quad_perm:[2,3,0,1] row_mask:0xf bank_mask:0xf
	v_add_f32_dpp v20, v20, v20 row_half_mirror row_mask:0xf bank_mask:0xf
	v_add_f32_dpp v21, v21, v21 row_half_mirror row_mask:0xf bank_mask:0xf
	v_add_f32_dpp v22, v22, v22 row_half_mirror row_mask:0xf bank_mask:0xf
	v_add_f32_dpp v23, v23, v23 row_half_mirror row_mask:0xf bank_mask:0xf
	v_add_f32_dpp v20, v20, v20 row_mirror row_mask:0xf bank_mask:0xf
	v_add_f32_dpp v21, v21, v21 row_mirror row_mask:0xf bank_mask:0xf
	v_add_f32_dpp v22, v22, v22 row_mirror row_mask:0xf bank_mask:0xf
	v_add_f32_dpp v23, v23, v23 row_mirror row_mask:0xf bank_mask:0xf
	v_mov_b32_e32 v16, v20
	v_mov_b32_e32 v17, v21
	v_mov_b32_e32 v18, v22
	v_mov_b32_e32 v19, v23
	v_permlane16_swap_b32_e32 v20, v16
	v_permlane16_swap_b32_e32 v21, v17
	v_permlane16_swap_b32_e32 v22, v18
	v_permlane16_swap_b32_e32 v23, v19
	v_add_f32_e32 v20, v20, v16
	v_add_f32_e32 v21, v21, v17
	v_add_f32_e32 v22, v22, v18
	v_add_f32_e32 v23, v23, v19
	v_mov_b32_e32 v16, v20
	v_mov_b32_e32 v17, v21
	v_mov_b32_e32 v18, v22
	v_mov_b32_e32 v19, v23
	v_permlane32_swap_b32_e32 v20, v16
	v_permlane32_swap_b32_e32 v21, v17
	v_permlane32_swap_b32_e32 v22, v18
	v_permlane32_swap_b32_e32 v23, v19
	v_add_f32_e32 v20, v20, v16
	v_add_f32_e32 v21, v21, v17
	v_add_f32_e32 v22, v22, v18
	v_add_f32_e32 v23, v23, v19
	v_mul_f32_e32 v20, 0x3b800000, v20
	v_mul_f32_e32 v21, 0x3b800000, v21
	v_mul_f32_e32 v22, 0x3b800000, v22
	v_mul_f32_e32 v23, 0x3b800000, v23
	v_add_f32_e32 v20, 0x358637bd, v20
	v_add_f32_e32 v21, 0x358637bd, v21
	v_add_f32_e32 v22, 0x358637bd, v22
	v_add_f32_e32 v23, 0x358637bd, v23
	v_rsq_f32_e32 v20, v20
	v_rsq_f32_e32 v21, v21
	v_rsq_f32_e32 v22, v22
	v_rsq_f32_e32 v23, v23
	v_mul_f32_e32 v0, v0, v20
	v_mul_f32_e32 v4, v4, v21
	v_mul_f32_e32 v8, v8, v22
	v_mul_f32_e32 v12, v12, v23
	v_mul_f32_e32 v1, v1, v20
	v_mul_f32_e32 v5, v5, v21
	v_mul_f32_e32 v9, v9, v22
	v_mul_f32_e32 v13, v13, v23
	v_mul_f32_e32 v2, v2, v20
	v_mul_f32_e32 v6, v6, v21
	v_mul_f32_e32 v10, v10, v22
	v_mul_f32_e32 v14, v14, v23
	v_mul_f32_e32 v3, v3, v20
	v_mul_f32_e32 v7, v7, v21
	v_mul_f32_e32 v11, v11, v22
	v_mul_f32_e32 v15, v15, v23
	v_fma_f32 v0, v0, v220, v224
	v_fma_f32 v4, v4, v220, v224
	v_fma_f32 v8, v8, v220, v224
	v_fma_f32 v12, v12, v220, v224
	v_fma_f32 v1, v1, v221, v225
	v_fma_f32 v5, v5, v221, v225
	v_fma_f32 v9, v9, v221, v225
	v_fma_f32 v13, v13, v221, v225
	v_fma_f32 v2, v2, v222, v226
	v_fma_f32 v6, v6, v222, v226
	v_fma_f32 v10, v10, v222, v226
	v_fma_f32 v14, v14, v222, v226
	v_fma_f32 v3, v3, v223, v227
	v_fma_f32 v7, v7, v223, v227
	v_fma_f32 v11, v11, v223, v227
	v_fma_f32 v15, v15, v223, v227
	v_mul_f32_e32 v48, 0xbfb8aa3b, v0
	v_mul_f32_e32 v52, 0xbfb8aa3b, v4
	v_mul_f32_e32 v56, 0xbfb8aa3b, v8
	v_mul_f32_e32 v60, 0xbfb8aa3b, v12
	v_mul_f32_e32 v49, 0xbfb8aa3b, v1
	v_mul_f32_e32 v53, 0xbfb8aa3b, v5
	v_mul_f32_e32 v57, 0xbfb8aa3b, v9
	v_mul_f32_e32 v61, 0xbfb8aa3b, v13
	v_mul_f32_e32 v50, 0xbfb8aa3b, v2
	v_mul_f32_e32 v54, 0xbfb8aa3b, v6
	v_mul_f32_e32 v58, 0xbfb8aa3b, v10
	v_mul_f32_e32 v62, 0xbfb8aa3b, v14
	v_mul_f32_e32 v51, 0xbfb8aa3b, v3
	v_mul_f32_e32 v55, 0xbfb8aa3b, v7
	v_mul_f32_e32 v59, 0xbfb8aa3b, v11
	v_mul_f32_e32 v63, 0xbfb8aa3b, v15
	v_exp_f32_e32 v48, v48
	v_exp_f32_e32 v52, v52
	v_exp_f32_e32 v56, v56
	v_exp_f32_e32 v60, v60
	v_exp_f32_e32 v49, v49
	v_exp_f32_e32 v53, v53
	v_exp_f32_e32 v57, v57
	v_exp_f32_e32 v61, v61
	v_exp_f32_e32 v50, v50
	v_exp_f32_e32 v54, v54
	v_exp_f32_e32 v58, v58
	v_exp_f32_e32 v62, v62
	v_exp_f32_e32 v51, v51
	v_exp_f32_e32 v55, v55
	v_exp_f32_e32 v59, v59
	v_exp_f32_e32 v63, v63
	v_add_f32_e32 v48, 1.0, v48
	v_add_f32_e32 v52, 1.0, v52
	v_add_f32_e32 v56, 1.0, v56
	v_add_f32_e32 v60, 1.0, v60
	v_add_f32_e32 v49, 1.0, v49
	v_add_f32_e32 v53, 1.0, v53
	v_add_f32_e32 v57, 1.0, v57
	v_add_f32_e32 v61, 1.0, v61
	v_add_f32_e32 v50, 1.0, v50
	v_add_f32_e32 v54, 1.0, v54
	v_add_f32_e32 v58, 1.0, v58
	v_add_f32_e32 v62, 1.0, v62
	v_add_f32_e32 v51, 1.0, v51
	v_add_f32_e32 v55, 1.0, v55
	v_add_f32_e32 v59, 1.0, v59
	v_add_f32_e32 v63, 1.0, v63
	v_rcp_f32_e32 v48, v48
	v_rcp_f32_e32 v52, v52
	v_rcp_f32_e32 v56, v56
	v_rcp_f32_e32 v60, v60
	v_rcp_f32_e32 v49, v49
	v_rcp_f32_e32 v53, v53
	v_rcp_f32_e32 v57, v57
	v_rcp_f32_e32 v61, v61
	v_rcp_f32_e32 v50, v50
	v_rcp_f32_e32 v54, v54
	v_rcp_f32_e32 v58, v58
	v_rcp_f32_e32 v62, v62
	v_rcp_f32_e32 v51, v51
	v_rcp_f32_e32 v55, v55
	v_rcp_f32_e32 v59, v59
	v_rcp_f32_e32 v63, v63
	v_mul_f32_e32 v0, v0, v48
	v_mul_f32_e32 v4, v4, v52
	v_mul_f32_e32 v8, v8, v56
	v_mul_f32_e32 v12, v12, v60
	v_mul_f32_e32 v1, v1, v49
	v_mul_f32_e32 v5, v5, v53
	v_mul_f32_e32 v9, v9, v57
	v_mul_f32_e32 v13, v13, v61
	v_mul_f32_e32 v2, v2, v50
	v_mul_f32_e32 v6, v6, v54
	v_mul_f32_e32 v10, v10, v58
	v_mul_f32_e32 v14, v14, v62
	v_mul_f32_e32 v3, v3, v51
	v_mul_f32_e32 v7, v7, v55
	v_mul_f32_e32 v11, v11, v59
	v_mul_f32_e32 v15, v15, v63
	v_cvt_pk_bf16_f32 v64, v0, v1
	v_cvt_pk_bf16_f32 v65, v2, v3
	v_cvt_pk_bf16_f32 v66, v4, v5
	v_cvt_pk_bf16_f32 v67, v6, v7
	v_cvt_pk_bf16_f32 v68, v8, v9
	v_cvt_pk_bf16_f32 v69, v10, v11
	v_cvt_pk_bf16_f32 v70, v12, v13
	v_cvt_pk_bf16_f32 v71, v14, v15
	global_store_dwordx2 v240, v[64:65], s[8:9] offset:0
	global_store_dwordx2 v240, v[66:67], s[8:9] offset:512
	global_store_dwordx2 v240, v[68:69], s[8:9] offset:1024
	global_store_dwordx2 v240, v[70:71], s[8:9] offset:1536
	s_add_u32 s4, s4, 0x100
	s_cmp_lt_u32 s4, s5
	s_cbranch_scc1 .Lcv_loop
	s_waitcnt vmcnt(0)
